# final pass walks each XCD's rows in reverse (the O rows written last by the out-GEMM are read first, from L2) and streams x with nt
# speedup vs baseline: 1.0024x; 1.0024x over previous
; __device__ __forceinline__ void final_pass(const Ptrs& P, int G) {
;     const int tid = threadIdx.x, lane = tid & 63, wave = tid >> 6;
;     const int gw = blockIdx.x * 8 + wave, NGW = G * 8;
;     const bf16_t* O = (const bf16_t*)(P.ws + WS_RB); const float* mod = (const float*)(P.ws + WS_MOD);
;     f32x4 gp[4];
; #pragma unroll
;     for (int j = 0; j < 4; ++j) gp[j] = *(const f32x4*)(P.g_post + 256 * j + 4 * lane);
;     for (int row0 = gw; row0 < T; row0 += 2 * NGW) {
;         u32x2 ov[2][4]; f32x4 xv[2][4], gt[2][4];
; #pragma unroll
;         for (int r = 0; r < 2; ++r) { const int row = row0 + r * NGW; if (row < T) { const int b = row >> 11;
;             const u32x2* op = (const u32x2*)(O + (size_t)row * DM) + lane; const f32x4* xr = (const f32x4*)(P.x + (size_t)row * DM) + lane;
; #pragma unroll
;             for (int j = 0; j < 4; ++j) { ov[r][j] = op[64 * j]; xv[r][j] = xr[64 * j]; gt[r][j] = *(const f32x4*)(mod + b * 3072 + 2048 + 256 * j + 4 * lane); } } }
.Lfin_j:
	v_cmp_gt_i32_e32 vcc, s8, v96
	s_and_saveexec_b64 s[0:1], vcc
	s_cbranch_execz .LBB0_1466
	v_and_b32_e32 v17, 63, v200
	v_readlane_b32 s12, v254, 7
	v_lshlrev_b32_e32 v16, 4, v17
	v_readlane_b32 s26, v254, 21
	v_readlane_b32 s27, v254, 22
	s_nop 4
	global_load_dwordx4 v[0:3], v16, s[26:27]
	global_load_dwordx4 v[4:7], v16, s[26:27] offset:1024
	global_load_dwordx4 v[8:11], v16, s[26:27] offset:2048
	global_load_dwordx4 v[12:15], v16, s[26:27] offset:3072
	v_lshlrev_b32_e32 v18, 2, v17
	v_lshlrev_b32_e32 v80, 3, v17
	v_mbcnt_lo_u32_b32 v17, -1, 0
	v_mov_b32_e32 v81, 0
	v_mbcnt_hi_u32_b32 v17, -1, v17
	v_lshl_add_u64 v[20:21], s[90:91], 0, v[80:81]
	s_mov_b64 s[0:1], 0x9000000
	v_and_b32_e32 v19, 64, v17
	v_lshl_add_u64 v[82:83], v[20:21], 0, s[0:1]
	v_add_u32_e32 v19, 64, v19
	v_xor_b32_e32 v20, 1, v17
	v_cmp_lt_i32_e32 vcc, v20, v19
	v_readlane_b32 s14, v254, 9
	v_readlane_b32 s15, v254, 10
	v_cndmask_b32_e32 v20, v17, v20, vcc
	v_lshlrev_b32_e32 v108, 2, v20
	v_xor_b32_e32 v20, 2, v17
	v_cmp_lt_i32_e32 vcc, v20, v19
	s_lshl_b32 s9, s83, 3
	s_cmp_eq_u32 s98, 0
	s_cselect_b32 s9, 0x100, s9
	s_mov_b64 s[2:3], 0
	v_cndmask_b32_e32 v20, v17, v20, vcc
	v_lshlrev_b32_e32 v109, 2, v20
	v_xor_b32_e32 v20, 4, v17
	v_cmp_lt_i32_e32 vcc, v20, v19
	v_lshlrev_b32_e32 v80, 2, v18
	s_mov_b64 s[4:5], 0x82000
	v_cndmask_b32_e32 v20, v17, v20, vcc
	v_lshlrev_b32_e32 v110, 2, v20
	v_xor_b32_e32 v20, 8, v17
	v_cmp_lt_i32_e32 vcc, v20, v19
	s_mov_b32 s10, 0x82000
	v_mov_b32_e32 v114, 0x358637bd
	v_cndmask_b32_e32 v20, v17, v20, vcc
	v_lshlrev_b32_e32 v111, 2, v20
	v_xor_b32_e32 v20, 16, v17
	v_cmp_lt_i32_e32 vcc, v20, v19
	s_add_i32 s11, s8, -1
	v_readlane_b32 s13, v254, 8
	v_cndmask_b32_e32 v20, v17, v20, vcc
	v_lshlrev_b32_e32 v112, 2, v20
	v_xor_b32_e32 v20, 32, v17
	v_cmp_lt_i32_e32 vcc, v20, v19
	v_readlane_b32 s16, v254, 11
	v_readlane_b32 s17, v254, 12
	v_cndmask_b32_e32 v17, v17, v20, vcc
	v_lshlrev_b32_e32 v113, 2, v17
	v_mov_b32_e32 v17, v81
	v_lshl_add_u64 v[84:85], s[48:49], 0, v[16:17]
	v_lshl_add_u64 v[86:87], s[88:89], 0, v[16:17]
	v_readlane_b32 s18, v254, 13
	v_readlane_b32 s19, v254, 14
	v_readlane_b32 s20, v254, 15
	v_readlane_b32 s21, v254, 16
	v_readlane_b32 s22, v254, 17
	v_readlane_b32 s23, v254, 18
	v_readlane_b32 s24, v254, 19
	v_readlane_b32 s25, v254, 20
	s_mov_b64 s[14:15], s[26:27]
	s_cmp_eq_u32 s98, 0
	s_cselect_b32 s99, -1, 1
	v_mov_b32_e32 v143, s99
	s_movk_i32 s99, 0xf00
	v_lshl_add_u32 v142, v96, 1, s99
	s_cselect_b32 s99, -1, 0
	v_and_b32_e32 v142, s99, v142
	s_branch .LBB0_1462

; __device__ __forceinline__ float bf_lo(unsigned w) { return __uint_as_float(w << 16); }
; __device__ __forceinline__ float bf_hi(unsigned w) { return __uint_as_float(w & 0xffff0000u); }
; __device__ __forceinline__ float sumsq4(f32x4 x) { return (x[0] * x[0] + x[1] * x[1]) + (x[2] * x[2] + x[3] * x[3]); }
; __device__ __forceinline__ void final_pass(const Ptrs& P, int G) {
;     ...
;     for (int row0 = gw; row0 < T; row0 += 2 * NGW) {
;         u32x2 ov[2][4]; f32x4 xv[2][4], gt[2][4];
; #pragma unroll
;         for (int r = 0; r < 2; ++r) { const int row = row0 + r * NGW; if (row < T) { const int b = row >> 11;
;             const u32x2* op = (const u32x2*)(O + (size_t)row * DM) + lane; const f32x4* xr = (const f32x4*)(P.x + (size_t)row * DM) + lane;
; #pragma unroll
;             for (int j = 0; j < 4; ++j) { ov[r][j] = op[64 * j]; xv[r][j] = xr[64 * j]; gt[r][j] = *(const f32x4*)(mod + b * 3072 + 2048 + 256 * j + 4 * lane); } } }
; #pragma unroll
;         for (int r = 0; r < 2; ++r) { const int row = row0 + r * NGW; if (row < T) {
;             f32x4 of[4]; float s = 0.f;
; #pragma unroll
;             for (int j = 0; j < 4; ++j) { of[j] = (f32x4){bf_lo(ov[r][j].x), bf_hi(ov[r][j].x), bf_lo(ov[r][j].y), bf_hi(ov[r][j].y)}; s += sumsq4(of[j]); }
;             const float rstd = __builtin_amdgcn_rsqf(wave_sum(s) * (1.0f / DM) + EPS);
;             f32x4* outp = (f32x4*)(P.out + (size_t)row * DM) + lane;
; #pragma unroll
;             for (int j = 0; j < 4; ++j) __builtin_nontemporal_store(xv[r][j] + gt[r][j] * gp[j] * of[j] * rstd, outp + 64 * j);
.LBB0_1462:
	v_ashrrev_i32_e32 v97, 31, v96
	v_mad_i32_i24 v140, v96, v143, v142
	v_ashrrev_i32_e32 v141, 31, v140
	v_ashrrev_i32_e32 v50, 11, v140
	v_lshlrev_b64 v[48:49], 11, v[140:141]
	v_lshl_add_u64 v[116:117], v[82:83], 0, v[48:49]
	v_mul_i32_i24_e32 v48, 0xc00, v50
	v_ashrrev_i32_e32 v49, 31, v48
	v_lshl_add_u64 v[48:49], v[48:49], 2, s[90:91]
	v_lshlrev_b64 v[98:99], 12, v[140:141]
	v_lshl_add_u64 v[48:49], v[48:49], 0, v[80:81]
	v_lshl_add_u64 v[118:119], v[84:85], 0, v[98:99]
	v_add_co_u32_e32 v122, vcc, s10, v48
	v_lshl_add_u64 v[120:121], v[48:49], 0, s[4:5]
	s_nop 0
	v_addc_co_u32_e32 v123, vcc, 0, v49, vcc
	global_load_dwordx4 v[72:75], v[118:119], off nt
	global_load_dwordx4 v[64:67], v[118:119], off offset:1024 nt
	global_load_dwordx4 v[68:71], v[120:121], off offset:1024
	global_load_dwordx4 v[60:63], v[120:121], off offset:2048
	global_load_dwordx2 v[106:107], v[116:117], off
	global_load_dwordx2 v[104:105], v[116:117], off offset:512
	global_load_dwordx2 v[102:103], v[116:117], off offset:1024
	global_load_dwordx2 v[100:101], v[116:117], off offset:1536
	global_load_dwordx4 v[56:59], v[118:119], off offset:2048 nt
	global_load_dwordx4 v[48:51], v[118:119], off offset:3072 nt
	global_load_dwordx4 v[76:79], v[122:123], off
	global_load_dwordx4 v[52:55], v[120:121], off offset:3072
	v_add_u32_e32 v96, s9, v96
	v_cmp_gt_i32_e64 s[0:1], s8, v96
	v_ashrrev_i32_e32 v97, 31, v96
	v_mad_i32_i24 v140, v96, v143, v142
	v_ashrrev_i32_e32 v141, 31, v140
	s_and_saveexec_b64 s[6:7], s[0:1]
	s_cbranch_execz .LBB0_1464
	v_lshlrev_b64 v[16:17], 11, v[140:141]
	v_ashrrev_i32_e32 v18, 11, v140
	v_lshl_add_u64 v[116:117], v[82:83], 0, v[16:17]
	v_lshlrev_b64 v[16:17], 12, v[140:141]
	v_lshl_add_u64 v[118:119], v[84:85], 0, v[16:17]
	v_mul_i32_i24_e32 v16, 0xc00, v18
	v_ashrrev_i32_e32 v17, 31, v16
	v_lshl_add_u64 v[16:17], v[16:17], 2, s[90:91]
	v_lshl_add_u64 v[16:17], v[16:17], 0, v[80:81]
	v_add_co_u32_e32 v122, vcc, 0x82000, v16
	v_lshl_add_u64 v[120:121], v[16:17], 0, s[4:5]
	s_nop 0
	v_addc_co_u32_e32 v123, vcc, 0, v17, vcc
	global_load_dwordx4 v[16:19], v[118:119], off nt
	global_load_dwordx4 v[20:23], v[118:119], off offset:1024 nt
	global_load_dwordx4 v[24:27], v[120:121], off offset:1024
	global_load_dwordx4 v[28:31], v[120:121], off offset:2048
	global_load_dwordx2 v[94:95], v[116:117], off
	global_load_dwordx2 v[92:93], v[116:117], off offset:512
	global_load_dwordx2 v[90:91], v[116:117], off offset:1024
	global_load_dwordx2 v[88:89], v[116:117], off offset:1536
	global_load_dwordx4 v[36:39], v[118:119], off offset:2048 nt
	global_load_dwordx4 v[32:35], v[118:119], off offset:3072 nt
	global_load_dwordx4 v[44:47], v[122:123], off
	global_load_dwordx4 v[40:43], v[120:121], off offset:3072
.LBB0_1464:
	s_or_b64 exec, exec, s[6:7]
	s_waitcnt vmcnt(0)
	v_lshlrev_b32_e32 v116, 16, v106
	v_and_b32_e32 v117, 0xffff0000, v106
	v_lshlrev_b32_e32 v106, 16, v107
	v_and_b32_e32 v107, 0xffff0000, v107
	v_mul_f32_e32 v118, v107, v107
	v_lshlrev_b32_e32 v121, 16, v105
	v_lshlrev_b32_e32 v120, 16, v104
	v_and_b32_e32 v105, 0xffff0000, v105
	v_and_b32_e32 v104, 0xffff0000, v104
	v_lshlrev_b32_e32 v127, 16, v100
	v_mul_f32_e32 v126, v117, v117
	v_pk_fma_f32 v[118:119], v[106:107], v[106:107], v[118:119] op_sel_hi:[1,1,0]
	v_pk_mul_f32 v[122:123], v[104:105], v[104:105]
	v_pk_fma_f32 v[130:131], v[116:117], v[116:117], v[126:127] op_sel_hi:[1,1,0]
	v_pk_fma_f32 v[122:123], v[120:121], v[120:121], v[122:123]
	v_and_b32_e32 v129, 0xffff0000, v100
	v_mov_b32_e32 v126, v130
	v_mov_b32_e32 v132, v118
	v_mov_b32_e32 v133, v127
	v_mul_f32_e32 v115, v129, v129
	v_pk_add_f32 v[118:119], v[130:131], v[118:119]
	v_pk_mul_f32 v[130:131], v[126:127], v[132:133]
	v_pk_add_f32 v[122:123], v[122:123], v[122:123] op_sel:[0,1] op_sel_hi:[1,0]
	v_lshlrev_b32_e32 v124, 16, v102
	v_and_b32_e32 v125, 0xffff0000, v102
	v_lshlrev_b32_e32 v102, 16, v103
	v_and_b32_e32 v103, 0xffff0000, v103
	v_mov_b32_e32 v119, v131
	v_mov_b32_e32 v123, v115
	v_lshlrev_b32_e32 v100, 16, v101
	v_and_b32_e32 v101, 0xffff0000, v101
	v_pk_add_f32 v[118:119], v[118:119], v[122:123]
	v_mul_f32_e32 v122, v125, v125
	v_mul_f32_e32 v126, v103, v103
	v_mul_f32_e32 v128, v100, v100
	v_mul_f32_e32 v134, v101, v101
	v_pk_fma_f32 v[122:123], v[124:125], v[124:125], v[122:123] op_sel_hi:[1,1,0]
	v_pk_fma_f32 v[130:131], v[102:103], v[102:103], v[126:127] op_sel_hi:[1,1,0]
	v_mov_b32_e32 v123, v128
	v_mov_b32_e32 v131, v134
	v_pk_add_f32 v[122:123], v[122:123], v[130:131]
	v_pk_mul_f32 v[78:79], v[2:3], v[78:79]
	v_pk_add_f32 v[118:119], v[118:119], v[122:123]
	v_pk_mul_f32 v[76:77], v[0:1], v[76:77]
	v_add_f32_e32 v115, v118, v119
	ds_bpermute_b32 v118, v108, v115
	v_pk_mul_f32 v[78:79], v[78:79], v[106:107]
	v_pk_mul_f32 v[76:77], v[76:77], v[116:117]
	v_lshl_add_u64 v[98:99], v[86:87], 0, v[98:99]
	v_pk_mul_f32 v[70:71], v[6:7], v[70:71]
	s_waitcnt lgkmcnt(0)
	v_add_f32_e32 v115, v115, v118
	ds_bpermute_b32 v118, v109, v115
	v_pk_mul_f32 v[68:69], v[4:5], v[68:69]
	v_pk_mul_f32 v[62:63], v[10:11], v[62:63]
	v_pk_mul_f32 v[60:61], v[8:9], v[60:61]
	v_pk_mul_f32 v[54:55], v[14:15], v[54:55]
	s_waitcnt lgkmcnt(0)
	v_add_f32_e32 v115, v115, v118
	ds_bpermute_b32 v118, v110, v115
	v_pk_mul_f32 v[52:53], v[12:13], v[52:53]
	v_mov_b32_e32 v128, v127
	v_pk_mul_f32 v[62:63], v[62:63], v[102:103]
	v_pk_mul_f32 v[60:61], v[60:61], v[124:125]
	s_waitcnt lgkmcnt(0)
	v_add_f32_e32 v115, v115, v118
	ds_bpermute_b32 v118, v111, v115
	v_pk_mul_f32 v[54:55], v[54:55], v[100:101]
	v_pk_mul_f32 v[52:53], v[52:53], v[128:129]
	s_waitcnt lgkmcnt(0)
	v_add_f32_e32 v115, v115, v118
	ds_bpermute_b32 v118, v112, v115
	s_waitcnt lgkmcnt(0)
	v_add_f32_e32 v115, v115, v118
	ds_bpermute_b32 v118, v113, v115
	s_waitcnt lgkmcnt(0)
	v_add_f32_e32 v115, v115, v118
	v_fmamk_f32 v115, v115, 0x3a800000, v114
	v_rsq_f32_e32 v118, v115
	s_nop 0
	v_pk_fma_f32 v[74:75], v[78:79], v[118:119], v[74:75] op_sel_hi:[1,0,1]
	v_pk_fma_f32 v[72:73], v[76:77], v[118:119], v[72:73] op_sel_hi:[1,0,1]
	global_store_dwordx4 v[98:99], v[72:75], off nt
	v_pk_fma_f32 v[58:59], v[62:63], v[118:119], v[58:59] op_sel_hi:[1,0,1]
	v_pk_fma_f32 v[56:57], v[60:61], v[118:119], v[56:57] op_sel_hi:[1,0,1]
	v_mov_b32_e32 v72, v121
	v_mov_b32_e32 v73, v105
	v_mov_b32_e32 v121, v104
	v_pk_mul_f32 v[70:71], v[70:71], v[72:73]
	v_pk_mul_f32 v[68:69], v[68:69], v[120:121]
	v_pk_fma_f32 v[66:67], v[70:71], v[118:119], v[66:67] op_sel_hi:[1,0,1]
	v_pk_fma_f32 v[64:65], v[68:69], v[118:119], v[64:65] op_sel_hi:[1,0,1]
	v_pk_fma_f32 v[50:51], v[54:55], v[118:119], v[50:51] op_sel_hi:[1,0,1]
	v_pk_fma_f32 v[48:49], v[52:53], v[118:119], v[48:49] op_sel_hi:[1,0,1]
	global_store_dwordx4 v[98:99], v[64:67], off offset:1024 nt
	global_store_dwordx4 v[98:99], v[56:59], off offset:2048 nt
	global_store_dwordx4 v[98:99], v[48:51], off offset:3072 nt
	s_and_saveexec_b64 s[6:7], s[0:1]
	s_cbranch_execz .LBB0_1461
; __device__ __forceinline__ float bf_lo(unsigned w) { return __uint_as_float(w << 16); }
; __device__ __forceinline__ float bf_hi(unsigned w) { return __uint_as_float(w & 0xffff0000u); }
; __device__ __forceinline__ float sumsq4(f32x4 x) { return (x[0] * x[0] + x[1] * x[1]) + (x[2] * x[2] + x[3] * x[3]); }
; __device__ __forceinline__ void final_pass(const Ptrs& P, int G) {
;     ...
;         for (int r = 0; r < 2; ++r) { const int row = row0 + r * NGW; if (row < T) {
;             f32x4 of[4]; float s = 0.f;
; #pragma unroll
;             for (int j = 0; j < 4; ++j) { of[j] = (f32x4){bf_lo(ov[r][j].x), bf_hi(ov[r][j].x), bf_lo(ov[r][j].y), bf_hi(ov[r][j].y)}; s += sumsq4(of[j]); }
;             const float rstd = __builtin_amdgcn_rsqf(wave_sum(s) * (1.0f / DM) + EPS);
;             f32x4* outp = (f32x4*)(P.out + (size_t)row * DM) + lane;
; #pragma unroll
;             for (int j = 0; j < 4; ++j) __builtin_nontemporal_store(xv[r][j] + gt[r][j] * gp[j] * of[j] * rstd, outp + 64 * j);
;         } }
	v_and_b32_e32 v51, 0xffff0000, v95
	v_and_b32_e32 v50, 0xffff0000, v94
	v_lshlrev_b32_e32 v49, 16, v95
	v_lshlrev_b32_e32 v48, 16, v94
	v_pk_mul_f32 v[52:53], v[50:51], v[50:51]
	v_and_b32_e32 v57, 0xffff0000, v93
	v_pk_fma_f32 v[52:53], v[48:49], v[48:49], v[52:53]
	v_and_b32_e32 v56, 0xffff0000, v92
	v_pk_add_f32 v[52:53], v[52:53], v[52:53] op_sel_hi:[0,1]
	v_lshlrev_b32_e32 v55, 16, v93
	v_lshlrev_b32_e32 v54, 16, v92
	v_pk_mul_f32 v[58:59], v[56:57], v[56:57]
	v_lshlrev_b32_e32 v60, 16, v90
	v_and_b32_e32 v61, 0xffff0000, v90
	v_lshlrev_b32_e32 v66, 16, v91
	v_lshlrev_b32_e32 v62, 16, v88
	v_pk_fma_f32 v[58:59], v[54:55], v[54:55], v[58:59]
	v_mul_f32_e32 v63, v60, v60
	v_mul_f32_e32 v65, v61, v61
	v_and_b32_e32 v67, 0xffff0000, v91
	v_mul_f32_e32 v52, v66, v66
	v_mov_b32_e32 v64, v62
	v_pk_add_f32 v[58:59], v[58:59], v[58:59] op_sel_hi:[0,1]
	v_pk_fma_f32 v[68:69], v[66:67], v[66:67], v[52:53] op_sel_hi:[1,1,0]
	v_and_b32_e32 v74, 0xffff0000, v88
	v_lshlrev_b32_e32 v70, 16, v89
	v_and_b32_e32 v71, 0xffff0000, v89
	v_pk_add_f32 v[64:65], v[62:63], v[64:65]
	v_mul_f32_e32 v68, v74, v74
	v_mul_f32_e32 v58, v70, v70
	v_mul_f32_e32 v52, v71, v71
	v_mul_f32_e32 v72, v62, v62
	v_mov_b32_e32 v73, v65
	v_pk_add_f32 v[64:65], v[72:73], v[68:69]
	v_pk_add_f32 v[52:53], v[58:59], v[52:53]
	v_pk_mul_f32 v[68:69], v[0:1], v[44:45]
	v_pk_add_f32 v[52:53], v[64:65], v[52:53]
	v_pk_mul_f32 v[64:65], v[2:3], v[46:47]
	v_add_f32_e32 v52, v52, v53
	ds_bpermute_b32 v53, v108, v52
	v_mov_b32_e32 v72, v49
	v_mov_b32_e32 v73, v51
	v_mov_b32_e32 v49, v50
	v_lshlrev_b64 v[58:59], 12, v[140:141]
	s_waitcnt lgkmcnt(0)
	v_add_f32_e32 v52, v52, v53
	ds_bpermute_b32 v53, v109, v52
	v_pk_mul_f32 v[64:65], v[64:65], v[72:73]
	v_pk_mul_f32 v[48:49], v[68:69], v[48:49]
	v_lshl_add_u64 v[58:59], v[86:87], 0, v[58:59]
	v_mov_b32_e32 v63, v74
	s_waitcnt lgkmcnt(0)
	v_add_f32_e32 v52, v52, v53
	ds_bpermute_b32 v53, v110, v52
	s_waitcnt lgkmcnt(0)
	v_add_f32_e32 v52, v52, v53
	ds_bpermute_b32 v53, v111, v52
	s_waitcnt lgkmcnt(0)
	v_add_f32_e32 v52, v52, v53
	ds_bpermute_b32 v53, v112, v52
	s_waitcnt lgkmcnt(0)
	v_add_f32_e32 v52, v52, v53
	ds_bpermute_b32 v53, v113, v52
	s_waitcnt lgkmcnt(0)
	v_add_f32_e32 v52, v52, v53
	v_fmamk_f32 v52, v52, 0x3a800000, v114
	v_rsq_f32_e32 v52, v52
	s_nop 0
	v_pk_fma_f32 v[50:51], v[64:65], v[52:53], v[18:19] op_sel_hi:[1,0,1]
	v_pk_fma_f32 v[48:49], v[48:49], v[52:53], v[16:17] op_sel_hi:[1,0,1]
	global_store_dwordx4 v[58:59], v[48:51], off nt
	v_mov_b32_e32 v64, v55
	v_mov_b32_e32 v65, v57
	v_pk_mul_f32 v[48:49], v[6:7], v[26:27]
	v_pk_mul_f32 v[50:51], v[4:5], v[24:25]
	v_mov_b32_e32 v55, v56
	v_pk_mul_f32 v[48:49], v[48:49], v[64:65]
	v_pk_mul_f32 v[54:55], v[50:51], v[54:55]
	v_pk_fma_f32 v[50:51], v[48:49], v[52:53], v[22:23] op_sel_hi:[1,0,1]
	v_pk_fma_f32 v[48:49], v[54:55], v[52:53], v[20:21] op_sel_hi:[1,0,1]
	global_store_dwordx4 v[58:59], v[48:51], off offset:1024 nt
	s_nop 1
	v_pk_mul_f32 v[48:49], v[10:11], v[30:31]
	v_pk_mul_f32 v[50:51], v[8:9], v[28:29]
	v_pk_mul_f32 v[48:49], v[66:67], v[48:49]
	v_pk_mul_f32 v[54:55], v[60:61], v[50:51]
	v_pk_fma_f32 v[50:51], v[48:49], v[52:53], v[38:39] op_sel_hi:[1,0,1]
	v_pk_fma_f32 v[48:49], v[54:55], v[52:53], v[36:37] op_sel_hi:[1,0,1]
	global_store_dwordx4 v[58:59], v[48:51], off offset:2048 nt
	s_nop 1
	v_pk_mul_f32 v[48:49], v[14:15], v[42:43]
	v_pk_mul_f32 v[50:51], v[12:13], v[40:41]
	v_pk_mul_f32 v[48:49], v[70:71], v[48:49]
	v_pk_mul_f32 v[54:55], v[62:63], v[50:51]
	v_pk_fma_f32 v[50:51], v[48:49], v[52:53], v[34:35] op_sel_hi:[1,0,1]
	v_pk_fma_f32 v[48:49], v[54:55], v[52:53], v[32:33] op_sel_hi:[1,0,1]
	global_store_dwordx4 v[58:59], v[48:51], off offset:3072 nt
	s_branch .LBB0_1461
